# ph14 dense ctx units: q-half index moved to bit 3 of the unit id so both halves of a (batch, head) share an XCD L2
# speedup vs baseline: 1.0098x; 1.0098x over previous
.LBB0_1760:
	s_cmpk_gt_i32 s86, 0x3ff
	s_mov_b64 s[4:5], -1
	s_cbranch_scc0 .LBB0_1778
	s_add_i32 s4, s86, 0xfffffc00
	s_lshr_b32 s4, s4, 5
	s_lshl_b32 s5, s86, 4
	s_lshr_b32 s8, s86, 1
	s_and_b32 s8, s8, 8
	s_and_b32 s9, s86, 7
	s_or_b32 s9, s9, s8
	s_lshl_b32 s80, s4, 8
	s_and_b32 s5, s5, 0x80
	s_mov_b32 s81, s25
	s_or_b32 s5, s80, s5
	s_lshl_b32 s8, s9, 6
	s_lshl_b32 s24, s9, 7
	s_lshl_b64 s[80:81], s[80:81], 11
	v_add_u32_e32 v2, s5, v102
	s_add_u32 s5, s14, s80
	s_addc_u32 s81, s15, s81
	s_add_u32 s80, s5, s24
	s_mov_b32 s5, s25
	v_mov_b32_e32 v3, v69
	s_addc_u32 s81, s81, 0
	s_lshl_b64 s[4:5], s[4:5], 19
	v_lshlrev_b64 v[4:5], 11, v[2:3]
	s_add_u32 s4, s16, s4
	v_lshl_add_u64 v[4:5], s[12:13], 0, v[4:5]
	s_addc_u32 s5, s17, s5
	s_lshl_b32 s9, s9, 15
	v_lshl_add_u64 v[4:5], v[4:5], 0, s[24:25]
	s_add_u32 s4, s4, s9
	v_mov_b32_e32 v93, v69
	s_addc_u32 s5, s5, 0
	v_lshl_add_u64 v[4:5], v[4:5], 0, v[92:93]
	v_lshl_add_u64 v[6:7], s[4:5], 0, v[70:71]
	global_load_dwordx4 v[50:53], v[4:5], off
	global_load_dwordx4 v[54:57], v[4:5], off offset:32
	global_load_dwordx4 v[58:61], v[4:5], off offset:64
	global_load_dwordx4 v[62:65], v[4:5], off offset:96
	v_lshl_add_u64 v[4:5], s[80:81], 0, v[66:67]
	v_readfirstlane_b32 s4, v104
	v_lshl_add_u64 v[98:99], v[4:5], 0, v[68:69]
	s_mov_b32 m0, s4
	v_readfirstlane_b32 s4, v125
	s_barrier
	global_load_lds_dwordx4 v[98:99], off
	v_lshl_add_u64 v[4:5], v[98:99], 0, s[34:35]
	s_mov_b32 m0, s4
	v_readfirstlane_b32 s4, v126
	v_lshl_add_u64 v[96:97], v[6:7], 0, v[68:69]
	global_load_lds_dwordx4 v[4:5], off
	s_mov_b32 m0, s4
	v_readfirstlane_b32 s4, v127
	global_load_lds_dwordx4 v[96:97], off
	v_lshl_add_u64 v[4:5], v[96:97], 0, s[36:37]
	s_mov_b32 m0, s4
	v_readfirstlane_b32 s4, v128
	global_load_lds_dwordx4 v[4:5], off
	v_lshl_add_u64 v[4:5], v[98:99], 0, s[38:39]
	s_mov_b32 m0, s4
	v_readfirstlane_b32 s4, v129
	s_waitcnt vmcnt(0)
	s_waitcnt vmcnt(0) lgkmcnt(0)
	s_barrier
	global_load_lds_dwordx4 v[4:5], off
	v_lshl_add_u64 v[4:5], v[98:99], 0, s[40:41]
	s_mov_b32 m0, s4
	v_readfirstlane_b32 s4, v130
	global_load_lds_dwordx4 v[4:5], off
	v_lshl_add_u64 v[4:5], v[96:97], 0, s[42:43]
	s_mov_b32 m0, s4
	v_readfirstlane_b32 s4, v131
	global_load_lds_dwordx4 v[4:5], off
	v_lshl_add_u64 v[4:5], v[96:97], 0, s[44:45]
	s_mov_b32 m0, s4
	v_cmp_lt_i32_e32 vcc, v134, v135
	global_load_lds_dwordx4 v[4:5], off
	v_lshlrev_b64 v[94:95], 10, v[2:3]
	v_cndmask_b32_e32 v2, v133, v134, vcc
	s_mov_b32 s9, 0
	v_lshlrev_b32_e32 v93, 2, v2
	v_mov_b32_e32 v18, v69
	v_mov_b32_e32 v19, v69
	v_mov_b32_e32 v20, v69
	v_mov_b32_e32 v21, v69
	v_mov_b32_e32 v22, v69
	v_mov_b32_e32 v23, v69
	v_mov_b32_e32 v24, v69
	v_mov_b32_e32 v25, v69
	v_mov_b32_e32 v26, v69
	v_mov_b32_e32 v27, v69
	v_mov_b32_e32 v28, v69
	v_mov_b32_e32 v29, v69
	v_mov_b32_e32 v30, v69
	v_mov_b32_e32 v31, v69
	v_mov_b32_e32 v32, v69
	v_mov_b32_e32 v33, v69
	v_mov_b32_e32 v2, v69
	v_mov_b32_e32 v4, v69
	v_mov_b32_e32 v5, v69
	v_mov_b32_e32 v6, v69
	v_mov_b32_e32 v7, v69
	v_mov_b32_e32 v8, v69
	v_mov_b32_e32 v9, v69
	v_mov_b32_e32 v10, v69
	v_mov_b32_e32 v11, v69
	v_mov_b32_e32 v12, v69
	v_mov_b32_e32 v13, v69
	v_mov_b32_e32 v14, v69
	v_mov_b32_e32 v15, v69
	v_mov_b32_e32 v16, v69
	v_mov_b32_e32 v17, v69
	s_mov_b64 s[4:5], -1
	v_mov_b32_e32 v100, 0
	v_mov_b32_e32 v101, 0xf149f2ca
	s_branch .LBB0_1763
